# output-phase epilogue: RMSNorm panel-stats publish store is a plain L2 store (the four exchanging workgroups share an XCD) instead of write-through
# speedup vs baseline: 1.0013x; 1.0013x over previous
.LBB0_939:
	s_or_b64 exec, exec, s[0:1]
	v_and_b32_e32 v0, 31, v0
	s_waitcnt lgkmcnt(0)
	s_barrier
	v_lshl_or_b32 v167, s2, 5, v0
	s_add_u32 s10, s82, 0x80000
	v_add_u32_e32 v130, s3, v167
	s_addc_u32 s11, s83, 0
	v_cmp_gt_u32_e64 s[0:1], 32, v147
	s_waitcnt lgkmcnt(0)
	v_ashrrev_i32_e32 v131, 31, v130
	s_and_saveexec_b64 s[2:3], s[0:1]
	s_cbranch_execz .LBB0_941
	v_lshl_add_u32 v0, v167, 5, 0
	ds_read_b128 v[132:135], v0
	ds_read_b128 v[136:139], v0 offset:16
	s_mov_b32 s5, 0
	s_lshl_b32 s4, s18, 3
	s_waitcnt lgkmcnt(1)
	v_add_f32_e32 v0, v132, v134
	s_waitcnt lgkmcnt(0)
	v_add_f32_e32 v0, v0, v136
	v_add_f32_e32 v1, v0, v138
	v_fmamk_f32 v132, v1, 0xbe800000, v132
	v_fmac_f32_e32 v134, 0xbe800000, v1
	v_fmamk_f32 v136, v1, 0xbe800000, v136
	v_fmac_f32_e32 v138, 0xbe800000, v1
	v_mul_f32_e32 v141, v132, v132
	v_mul_f32_e32 v143, v134, v134
	v_mul_f32_e32 v145, v136, v136
	v_mul_f32_e32 v169, v138, v138
	v_mov_b32_e32 v140, v133
	v_mov_b32_e32 v142, v135
	v_mov_b32_e32 v144, v137
	v_mov_b32_e32 v168, v139
	v_pk_add_f32 v[132:133], v[140:141], v[142:143]
	v_pk_add_f32 v[134:135], v[144:145], v[168:169]
	v_mul_f32_e32 v0, 0x3e800000, v1
	v_pk_add_f32 v[132:133], v[132:133], v[134:135]
	s_nop 0
	v_fmamk_f32 v1, v133, 0x42800000, v132
	v_lshlrev_b64 v[132:133], 5, v[130:131]
	v_lshl_add_u64 v[132:133], s[10:11], 0, v[132:133]
	v_lshl_add_u64 v[132:133], v[132:133], 0, s[4:5]
	global_store_dwordx2 v[132:133], v[0:1], off
